# early buffer_wbl2 by thread 0 of every WG on barrier arrival (overlap L2 writeback with stragglers)
# baseline (speedup 1.0000x reference)
.LBB0_1459:
	s_waitcnt vmcnt(0) expcnt(0) lgkmcnt(0)
	buffer_wbl2 sc1
	ds_read_b32 v3, v1
	ds_read_b32 v2, v1 offset:4
	s_waitcnt lgkmcnt(1)
	v_cmp_ne_u32_e32 vcc, 0, v3
	s_cbranch_vccnz .LBB0_1474
	v_readlane_b32 s4, v251, 20
	v_readlane_b32 s5, v251, 21
	s_load_dwordx2 s[2:3], s[4:5], 0x0
	s_nop 0
	s_load_dword s4, s[4:5], 0x8
	s_mov_b32 s9, 1
	s_waitcnt lgkmcnt(0)
	s_mul_i32 s8, s3, s2
	s_mul_i32 s8, s8, s4
	s_branch .LBB0_1462
